# non-temporal hints on the one-time streaming accesses (prologue f32 weight loads, final-norm f32 output stores), on top of v49
# baseline (speedup 1.0000x reference)
.LBB0_15:
	s_mul_hi_i32 s10, s35, 0xb21642c9
	s_add_i32 s10, s10, s35
	s_lshr_b32 s11, s10, 31
	s_ashr_i32 s10, s10, 14
	s_add_i32 s10, s10, s11
	s_mul_i32 s11, s10, 0xffffa400
	s_add_i32 s11, s35, s11
	s_cmpk_gt_i32 s11, 0xfff
	s_mov_b64 s[26:27], -1
	s_cbranch_scc0 .LBB0_25
	s_cmpk_gt_u32 s11, 0x19ff
	s_cbranch_scc0 .LBB0_22
	s_cmpk_gt_u32 s11, 0x45ff
	s_mul_hi_i32 s36, s10, 0x2c00000
	s_mul_i32 s37, s10, 0x2c00000
	s_cbranch_scc0 .LBB0_19
	s_load_dwordx2 s[26:27], s[22:23], 0xa0
	s_and_b32 s12, s11, 0x7fffffc0
	s_addk_i32 s12, 0xba00
	s_mul_hi_i32 s13, s10, 0x1600000
	v_or_b32_e32 v56, s12, v6
	s_waitcnt lgkmcnt(0)
	s_add_u32 s24, s26, s37
	s_addc_u32 s27, s27, s36
	s_and_b32 s38, s33, 0x7e0
	s_mul_i32 s26, s10, 0x1600000
	s_add_u32 s39, s6, s26
	s_addc_u32 s13, s7, s13
	s_lshl_b32 s26, s38, 2
	s_add_u32 s26, s24, s26
	s_addc_u32 s27, s27, 0
	v_mov_b32_e32 v57, v3
	v_or_b32_e32 v30, 8, v56
	v_mov_b32_e32 v31, v3
	v_or_b32_e32 v36, 16, v56
	v_mov_b32_e32 v37, v3
	v_or_b32_e32 v38, 24, v56
	v_mov_b32_e32 v39, v3
	v_or_b32_e32 v44, 32, v56
	v_mov_b32_e32 v45, v3
	v_or_b32_e32 v46, 40, v56
	v_mov_b32_e32 v47, v3
	v_lshl_add_u64 v[58:59], s[26:27], 0, v[2:3]
	v_lshlrev_b64 v[28:29], 13, v[56:57]
	v_lshlrev_b64 v[30:31], 13, v[30:31]
	v_lshlrev_b64 v[36:37], 13, v[36:37]
	v_lshlrev_b64 v[38:39], 13, v[38:39]
	v_lshlrev_b64 v[44:45], 13, v[44:45]
	v_lshlrev_b64 v[46:47], 13, v[46:47]
	v_lshl_add_u64 v[28:29], v[58:59], 0, v[28:29]
	v_lshl_add_u64 v[32:33], v[58:59], 0, v[30:31]
	v_lshl_add_u64 v[36:37], v[58:59], 0, v[36:37]
	v_lshl_add_u64 v[40:41], v[58:59], 0, v[38:39]
	v_lshl_add_u64 v[44:45], v[58:59], 0, v[44:45]
	v_lshl_add_u64 v[48:49], v[58:59], 0, v[46:47]
	global_load_dwordx4 v[28:31], v[28:29], off nt
	s_nop 0
	global_load_dwordx4 v[32:35], v[32:33], off nt
	s_nop 0
	global_load_dwordx4 v[36:39], v[36:37], off nt
	s_nop 0
	global_load_dwordx4 v[40:43], v[40:41], off nt
	s_nop 0
	global_load_dwordx4 v[44:47], v[44:45], off nt
	s_nop 0
	global_load_dwordx4 v[48:51], v[48:49], off nt
	v_or_b32_e32 v52, 48, v56
	v_mov_b32_e32 v53, v3
	v_lshlrev_b64 v[52:53], 13, v[52:53]
	v_lshl_add_u64 v[52:53], v[58:59], 0, v[52:53]
	v_or_b32_e32 v56, 56, v56
	global_load_dwordx4 v[52:55], v[52:53], off nt
	v_lshlrev_b64 v[56:57], 13, v[56:57]
	v_lshl_add_u64 v[56:57], v[58:59], 0, v[56:57]
	global_load_dwordx4 v[56:59], v[56:57], off nt
	s_bfe_u32 s24, s33, 0x30008
	s_lshr_b32 s12, s12, 6
	s_mulk_i32 s24, 0x58
	s_add_i32 s24, s24, s12
	s_lshl_b64 s[26:27], s[24:25], 15
	s_add_u32 s26, s39, s26
	s_addc_u32 s27, s13, s27
	v_mov_b32_e32 v5, v3
	s_waitcnt vmcnt(7)
	ds_write2_b32 v12, v28, v29 offset1:1
	ds_write2_b32 v12, v30, v31 offset0:2 offset1:3
	s_waitcnt vmcnt(6)
	ds_write2_b32 v13, v32, v33 offset1:1
	ds_write2_b32 v14, v34, v35 offset1:1
	s_waitcnt vmcnt(5)
	ds_write2_b32 v15, v36, v37 offset1:1
	ds_write2_b32 v16, v38, v39 offset1:1
	s_waitcnt vmcnt(4)
	ds_write2_b32 v17, v40, v41 offset1:1
	ds_write2_b32 v18, v42, v43 offset1:1
	s_waitcnt vmcnt(3)
	ds_write2_b32 v19, v44, v45 offset1:1
	ds_write2_b32 v20, v46, v47 offset1:1
	s_waitcnt vmcnt(2)
	ds_write2_b32 v21, v48, v49 offset1:1
	ds_write2_b32 v22, v50, v51 offset1:1
	s_waitcnt vmcnt(1)
	ds_write2_b32 v23, v52, v53 offset1:1
	ds_write2_b32 v24, v54, v55 offset1:1
	s_waitcnt vmcnt(0)
	ds_write2_b32 v25, v56, v57 offset1:1
	ds_write2_b32 v27, v58, v59 offset1:1
	s_waitcnt lgkmcnt(0)
	v_or_b32_e32 v32, s38, v6
	ds_read2_b32 v[28:29], v10 offset1:33
	v_lshlrev_b32_e32 v32, 7, v32
	s_waitcnt lgkmcnt(0)
	v_cvt_pk_bf16_f32 v28, v28, v29
	ds_read2_b32 v[30:31], v10 offset0:66 offset1:99
	v_mov_b32_e32 v33, v3
	v_and_b32_e32 v32, 0x7380, v32
	s_waitcnt lgkmcnt(0)
	v_cvt_pk_bf16_f32 v29, v30, v31
	ds_read2_b32 v[30:31], v10 offset0:132 offset1:165
	v_lshl_add_u64 v[32:33], s[26:27], 0, v[32:33]
	s_waitcnt lgkmcnt(0)
	v_cvt_pk_bf16_f32 v30, v30, v31
	ds_read2_b32 v[34:35], v10 offset0:198 offset1:231
	s_waitcnt lgkmcnt(0)
	v_cvt_pk_bf16_f32 v31, v34, v35
	v_lshl_add_u64 v[32:33], v[32:33], 0, v[4:5]
	ds_read2_b32 v[34:35], v10 offset0:8 offset1:41
	global_store_dwordx4 v[32:33], v[28:31], off
	s_waitcnt lgkmcnt(0)
	s_nop 0
	v_cvt_pk_bf16_f32 v28, v34, v35
	ds_read2_b32 v[30:31], v10 offset0:74 offset1:107
	s_waitcnt lgkmcnt(0)
	v_cvt_pk_bf16_f32 v29, v30, v31
	ds_read2_b32 v[30:31], v10 offset0:140 offset1:173
	s_waitcnt lgkmcnt(0)
	v_cvt_pk_bf16_f32 v30, v30, v31
	v_or_b32_e32 v31, s38, v7
	v_lshlrev_b32_e32 v34, 7, v31
	v_mov_b32_e32 v35, v3
	v_and_b32_e32 v34, 0x7780, v34
	v_lshl_add_u64 v[34:35], s[26:27], 0, v[34:35]
	ds_read2_b32 v[32:33], v10 offset0:206 offset1:239
	s_waitcnt lgkmcnt(0)
	v_cvt_pk_bf16_f32 v31, v32, v33
	v_lshl_add_u64 v[34:35], v[34:35], 0, v[4:5]
	ds_read2_b32 v[32:33], v10 offset0:16 offset1:49
	global_store_dwordx4 v[34:35], v[28:31], off
	v_mov_b32_e32 v35, v3
	s_waitcnt lgkmcnt(0)
	v_cvt_pk_bf16_f32 v28, v32, v33
	ds_read2_b32 v[30:31], v10 offset0:82 offset1:115
	s_waitcnt lgkmcnt(0)
	v_cvt_pk_bf16_f32 v29, v30, v31
	ds_read2_b32 v[30:31], v10 offset0:148 offset1:181
	s_waitcnt lgkmcnt(0)
	v_cvt_pk_bf16_f32 v30, v30, v31
	v_or_b32_e32 v31, s38, v8
	v_lshlrev_b32_e32 v34, 7, v31
	v_and_b32_e32 v34, 0x7b80, v34
	v_lshl_add_u64 v[34:35], s[26:27], 0, v[34:35]
	ds_read2_b32 v[32:33], v10 offset0:214 offset1:247
	s_waitcnt lgkmcnt(0)
	v_cvt_pk_bf16_f32 v31, v32, v33
	v_lshl_add_u64 v[34:35], v[34:35], 0, v[4:5]
	ds_read2_b32 v[32:33], v10 offset0:24 offset1:57
	global_store_dwordx4 v[34:35], v[28:31], off
	s_waitcnt lgkmcnt(0)
	s_nop 0
	v_cvt_pk_bf16_f32 v28, v32, v33
	ds_read2_b32 v[30:31], v10 offset0:90 offset1:123
	s_waitcnt lgkmcnt(0)
	v_cvt_pk_bf16_f32 v29, v30, v31
	ds_read2_b32 v[30:31], v10 offset0:156 offset1:189
	s_waitcnt lgkmcnt(0)
	v_cvt_pk_bf16_f32 v30, v30, v31
	v_or_b32_e32 v31, s38, v9
	v_lshlrev_b32_e32 v31, 7, v31
	v_mov_b32_e32 v33, v3
	v_and_b32_e32 v32, 0x7f80, v31
	v_lshl_add_u64 v[32:33], s[26:27], 0, v[32:33]
	v_lshl_add_u64 v[32:33], v[32:33], 0, v[4:5]
	ds_read2_b32 v[34:35], v10 offset0:222 offset1:255
	s_waitcnt lgkmcnt(0)
	v_cvt_pk_bf16_f32 v31, v34, v35
	global_store_dwordx4 v[32:33], v[28:31], off
	s_waitcnt lgkmcnt(0)
	s_mov_b64 s[26:27], 0
.LBB0_19:
	s_andn2_b64 vcc, exec, s[26:27]
	s_cbranch_vccnz .LBB0_21
	s_add_i32 s12, s11, 0xe600
	s_and_b32 s13, s12, 0xffff
	s_mul_i32 s13, s13, 0xba2f
	s_lshr_b32 s13, s13, 24
	s_mul_i32 s24, s13, 0x160
	s_sub_i32 s12, s12, s24
	s_and_b32 s26, s12, 0xffff
	s_lshl_b32 s24, s26, 5
	s_bfe_i32 s27, s12, 0x10002
	s_lshl_b32 s26, s26, 4
	s_and_b32 s27, s27, 0x1600
	s_and_b32 s26, s26, 0x1f80
	s_add_i32 s38, s27, s26
	s_load_dwordx2 s[26:27], s[22:23], 0x88
	s_and_b32 s39, s24, 0x60
	s_or_b32 s38, s38, s39
	s_mul_i32 s40, s10, 0x5800000
	s_mul_hi_i32 s39, s10, 0x5800000
	s_waitcnt lgkmcnt(0)
	s_add_u32 s26, s26, s40
	s_addc_u32 s27, s27, s39
	s_add_u32 s37, s8, s37
	s_addc_u32 s36, s9, s36
	s_lshl_b32 s38, s38, 2
	v_lshl_or_b32 v5, s13, 6, v6
	s_add_u32 s26, s26, s38
	s_addc_u32 s27, s27, 0
	v_mul_u32_u24_e32 v5, 0x2c00, v5
	v_lshl_add_u64 v[28:29], s[26:27], 0, v[2:3]
	v_lshlrev_b32_e32 v30, 2, v5
	v_mov_b32_e32 v31, v3
	v_lshl_add_u64 v[56:57], v[28:29], 0, v[30:31]
	s_mov_b32 s26, 0x58000
	v_add_co_u32_e32 v32, vcc, s26, v56
	s_mov_b32 s26, 0xb0000
	s_nop 0
	v_addc_co_u32_e32 v33, vcc, 0, v57, vcc
	v_add_co_u32_e32 v36, vcc, s26, v56
	s_mov_b32 s26, 0x108000
	s_nop 0
	v_addc_co_u32_e32 v37, vcc, 0, v57, vcc
	v_add_co_u32_e32 v40, vcc, s26, v56
	s_mov_b32 s26, 0x160000
	s_nop 0
	v_addc_co_u32_e32 v41, vcc, 0, v57, vcc
	v_add_co_u32_e32 v44, vcc, s26, v56
	s_mov_b32 s26, 0x1b8000
	s_nop 0
	v_addc_co_u32_e32 v45, vcc, 0, v57, vcc
	v_add_co_u32_e32 v48, vcc, s26, v56
	global_load_dwordx4 v[28:31], v[56:57], off nt
	s_nop 0
	global_load_dwordx4 v[32:35], v[32:33], off nt
	v_addc_co_u32_e32 v49, vcc, 0, v57, vcc
	global_load_dwordx4 v[36:39], v[36:37], off nt
	s_nop 0
	global_load_dwordx4 v[40:43], v[40:41], off nt
	s_nop 0
	global_load_dwordx4 v[44:47], v[44:45], off nt
	s_nop 0
	global_load_dwordx4 v[48:51], v[48:49], off nt
	s_mov_b32 s26, 0x210000
	v_add_co_u32_e32 v52, vcc, s26, v56
	s_mov_b32 s26, 0x268000
	s_nop 0
	v_addc_co_u32_e32 v53, vcc, 0, v57, vcc
	global_load_dwordx4 v[52:55], v[52:53], off nt
	v_add_co_u32_e32 v56, vcc, s26, v56
	s_lshl_b32 s12, s12, 2
	s_nop 0
	v_addc_co_u32_e32 v57, vcc, 0, v57, vcc
	global_load_dwordx4 v[56:59], v[56:57], off nt
	s_and_b32 s12, s12, 0x7e0
	s_add_i32 s12, s12, s13
	s_lshl_b32 s12, s12, 15
	s_add_u32 s26, s37, s12
	s_addc_u32 s27, s36, 0
	v_mov_b32_e32 v5, v3
	s_waitcnt vmcnt(7)
	ds_write2_b32 v12, v28, v29 offset1:1
	ds_write2_b32 v12, v30, v31 offset0:2 offset1:3
	s_waitcnt vmcnt(6)
	ds_write2_b32 v13, v32, v33 offset1:1
	ds_write2_b32 v14, v34, v35 offset1:1
	s_waitcnt vmcnt(5)
	ds_write2_b32 v15, v36, v37 offset1:1
	ds_write2_b32 v16, v38, v39 offset1:1
	s_waitcnt vmcnt(4)
	ds_write2_b32 v17, v40, v41 offset1:1
	ds_write2_b32 v18, v42, v43 offset1:1
	s_waitcnt vmcnt(3)
	ds_write2_b32 v19, v44, v45 offset1:1
	ds_write2_b32 v20, v46, v47 offset1:1
	s_waitcnt vmcnt(2)
	ds_write2_b32 v21, v48, v49 offset1:1
	ds_write2_b32 v22, v50, v51 offset1:1
	s_waitcnt vmcnt(1)
	ds_write2_b32 v23, v52, v53 offset1:1
	ds_write2_b32 v24, v54, v55 offset1:1
	s_waitcnt vmcnt(0)
	ds_write2_b32 v25, v56, v57 offset1:1
	ds_write2_b32 v27, v58, v59 offset1:1
	s_waitcnt lgkmcnt(0)
	v_or_b32_e32 v32, s24, v6
	ds_read2_b32 v[28:29], v10 offset1:33
	v_lshlrev_b32_e32 v32, 7, v32
	s_waitcnt lgkmcnt(0)
	v_cvt_pk_bf16_f32 v28, v28, v29
	ds_read2_b32 v[30:31], v10 offset0:66 offset1:99
	v_mov_b32_e32 v33, v3
	v_and_b32_e32 v32, 0x7380, v32
	s_waitcnt lgkmcnt(0)
	v_cvt_pk_bf16_f32 v29, v30, v31
	ds_read2_b32 v[30:31], v10 offset0:132 offset1:165
	v_lshl_add_u64 v[32:33], s[26:27], 0, v[32:33]
	s_waitcnt lgkmcnt(0)
	v_cvt_pk_bf16_f32 v30, v30, v31
	ds_read2_b32 v[34:35], v10 offset0:198 offset1:231
	s_waitcnt lgkmcnt(0)
	v_cvt_pk_bf16_f32 v31, v34, v35
	v_lshl_add_u64 v[32:33], v[32:33], 0, v[4:5]
	ds_read2_b32 v[34:35], v10 offset0:8 offset1:41
	global_store_dwordx4 v[32:33], v[28:31], off
	s_waitcnt lgkmcnt(0)
	s_nop 0
	v_cvt_pk_bf16_f32 v28, v34, v35
	ds_read2_b32 v[30:31], v10 offset0:74 offset1:107
	s_waitcnt lgkmcnt(0)
	v_cvt_pk_bf16_f32 v29, v30, v31
	ds_read2_b32 v[30:31], v10 offset0:140 offset1:173
	s_waitcnt lgkmcnt(0)
	v_cvt_pk_bf16_f32 v30, v30, v31
	v_or_b32_e32 v31, s24, v7
	v_lshlrev_b32_e32 v34, 7, v31
	v_mov_b32_e32 v35, v3
	v_and_b32_e32 v34, 0x7780, v34
	v_lshl_add_u64 v[34:35], s[26:27], 0, v[34:35]
	ds_read2_b32 v[32:33], v10 offset0:206 offset1:239
	s_waitcnt lgkmcnt(0)
	v_cvt_pk_bf16_f32 v31, v32, v33
	v_lshl_add_u64 v[34:35], v[34:35], 0, v[4:5]
	ds_read2_b32 v[32:33], v10 offset0:16 offset1:49
	global_store_dwordx4 v[34:35], v[28:31], off
	v_mov_b32_e32 v35, v3
	s_waitcnt lgkmcnt(0)
	v_cvt_pk_bf16_f32 v28, v32, v33
	ds_read2_b32 v[30:31], v10 offset0:82 offset1:115
	s_waitcnt lgkmcnt(0)
	v_cvt_pk_bf16_f32 v29, v30, v31
	ds_read2_b32 v[30:31], v10 offset0:148 offset1:181
	s_waitcnt lgkmcnt(0)
	v_cvt_pk_bf16_f32 v30, v30, v31
	v_or_b32_e32 v31, s24, v8
	v_lshlrev_b32_e32 v34, 7, v31
	v_and_b32_e32 v34, 0x7b80, v34
	v_lshl_add_u64 v[34:35], s[26:27], 0, v[34:35]
	ds_read2_b32 v[32:33], v10 offset0:214 offset1:247
	s_waitcnt lgkmcnt(0)
	v_cvt_pk_bf16_f32 v31, v32, v33
	v_lshl_add_u64 v[34:35], v[34:35], 0, v[4:5]
	ds_read2_b32 v[32:33], v10 offset0:24 offset1:57
	global_store_dwordx4 v[34:35], v[28:31], off
	s_waitcnt lgkmcnt(0)
	s_nop 0
	v_cvt_pk_bf16_f32 v28, v32, v33
	ds_read2_b32 v[30:31], v10 offset0:90 offset1:123
	s_waitcnt lgkmcnt(0)
	v_cvt_pk_bf16_f32 v29, v30, v31
	ds_read2_b32 v[30:31], v10 offset0:156 offset1:189
	s_waitcnt lgkmcnt(0)
	v_cvt_pk_bf16_f32 v30, v30, v31
	v_or_b32_e32 v31, s24, v9
	v_lshlrev_b32_e32 v31, 7, v31
	v_mov_b32_e32 v33, v3
	v_and_b32_e32 v32, 0x7f80, v31
	v_lshl_add_u64 v[32:33], s[26:27], 0, v[32:33]
	v_lshl_add_u64 v[32:33], v[32:33], 0, v[4:5]
	ds_read2_b32 v[34:35], v10 offset0:222 offset1:255
	s_waitcnt lgkmcnt(0)
	v_cvt_pk_bf16_f32 v31, v34, v35
	global_store_dwordx4 v[32:33], v[28:31], off
	s_waitcnt lgkmcnt(0)

.LBB0_22:
	s_andn2_b64 vcc, exec, s[26:27]
	s_cbranch_vccnz .LBB0_24
	s_load_dwordx2 s[26:27], s[22:23], 0x80
	s_and_b32 s12, s11, 0x1fc0
	s_mul_i32 s24, s10, 0x1400000
	s_addk_i32 s12, 0xf000
	s_mul_hi_i32 s13, s10, 0x1400000
	s_waitcnt lgkmcnt(0)
	s_add_u32 s24, s26, s24
	s_addc_u32 s13, s27, s13
	s_and_b32 s26, s33, 0x7e0
	s_mul_i32 s36, s10, 0xa00000
	s_mul_hi_i32 s27, s10, 0xa00000
	s_add_u32 s36, s19, s36
	s_addc_u32 s37, s28, s27
	s_lshl_b32 s26, s26, 2
	v_or_b32_e32 v56, s12, v6
	s_add_u32 s26, s24, s26
	s_addc_u32 s27, s13, 0
	v_mov_b32_e32 v57, v3
	v_or_b32_e32 v30, 8, v56
	v_mov_b32_e32 v31, v3
	v_or_b32_e32 v36, 16, v56
	v_mov_b32_e32 v37, v3
	v_or_b32_e32 v38, 24, v56
	v_mov_b32_e32 v39, v3
	v_or_b32_e32 v44, 32, v56
	v_mov_b32_e32 v45, v3
	v_or_b32_e32 v46, 40, v56
	v_mov_b32_e32 v47, v3
	v_lshl_add_u64 v[58:59], s[26:27], 0, v[2:3]
	v_lshlrev_b64 v[28:29], 13, v[56:57]
	v_lshlrev_b64 v[30:31], 13, v[30:31]
	v_lshlrev_b64 v[36:37], 13, v[36:37]
	v_lshlrev_b64 v[38:39], 13, v[38:39]
	v_lshlrev_b64 v[44:45], 13, v[44:45]
	v_lshlrev_b64 v[46:47], 13, v[46:47]
	v_lshl_add_u64 v[28:29], v[58:59], 0, v[28:29]
	v_lshl_add_u64 v[32:33], v[58:59], 0, v[30:31]
	v_lshl_add_u64 v[36:37], v[58:59], 0, v[36:37]
	v_lshl_add_u64 v[40:41], v[58:59], 0, v[38:39]
	v_lshl_add_u64 v[44:45], v[58:59], 0, v[44:45]
	v_lshl_add_u64 v[48:49], v[58:59], 0, v[46:47]
	global_load_dwordx4 v[28:31], v[28:29], off nt
	s_nop 0
	global_load_dwordx4 v[32:35], v[32:33], off nt
	s_nop 0
	global_load_dwordx4 v[36:39], v[36:37], off nt
	s_nop 0
	global_load_dwordx4 v[40:43], v[40:41], off nt
	s_nop 0
	global_load_dwordx4 v[44:47], v[44:45], off nt
	s_nop 0
	global_load_dwordx4 v[48:51], v[48:49], off nt
	v_or_b32_e32 v52, 48, v56
	v_mov_b32_e32 v53, v3
	v_lshlrev_b64 v[52:53], 13, v[52:53]
	v_lshl_add_u64 v[52:53], v[58:59], 0, v[52:53]
	v_or_b32_e32 v56, 56, v56
	global_load_dwordx4 v[52:55], v[52:53], off nt
	v_lshlrev_b64 v[56:57], 13, v[56:57]
	v_lshl_add_u64 v[56:57], v[58:59], 0, v[56:57]
	global_load_dwordx4 v[56:59], v[56:57], off nt
	s_mul_i32 s13, s10, 0xfd200000
	s_lshr_b32 s12, s12, 6
	v_mov_b32_e32 v5, v3
	s_waitcnt vmcnt(7)
	ds_write2_b32 v12, v28, v29 offset1:1
	ds_write2_b32 v12, v30, v31 offset0:2 offset1:3
	s_waitcnt vmcnt(6)
	ds_write2_b32 v13, v32, v33 offset1:1
	ds_write2_b32 v14, v34, v35 offset1:1
	s_waitcnt vmcnt(5)
	ds_write2_b32 v15, v36, v37 offset1:1
	ds_write2_b32 v16, v38, v39 offset1:1
	s_waitcnt vmcnt(4)
	ds_write2_b32 v17, v40, v41 offset1:1
	ds_write2_b32 v18, v42, v43 offset1:1
	s_waitcnt vmcnt(3)
	ds_write2_b32 v19, v44, v45 offset1:1
	ds_write2_b32 v20, v46, v47 offset1:1
	s_waitcnt vmcnt(2)
	ds_write2_b32 v21, v48, v49 offset1:1
	ds_write2_b32 v22, v50, v51 offset1:1
	s_waitcnt vmcnt(1)
	ds_write2_b32 v23, v52, v53 offset1:1
	ds_write2_b32 v24, v54, v55 offset1:1
	s_waitcnt vmcnt(0)
	ds_write2_b32 v25, v56, v57 offset1:1
	ds_write2_b32 v27, v58, v59 offset1:1
	v_add_u32_e32 v36, s13, v11
	s_bfe_u32 s13, s33, 0x30008
	s_mul_i32 s13, s13, 40
	s_waitcnt lgkmcnt(0)
	s_add_i32 s24, s13, s12
	s_lshl_b64 s[26:27], s[24:25], 15
	ds_read2_b32 v[28:29], v10 offset1:33
	v_and_b32_e32 v32, 0x39c0, v36
	s_add_u32 s26, s36, s26
	s_waitcnt lgkmcnt(0)
	v_cvt_pk_bf16_f32 v28, v28, v29
	ds_read2_b32 v[30:31], v10 offset0:66 offset1:99
	v_mov_b32_e32 v33, v3
	v_lshlrev_b32_e32 v32, 1, v32
	s_addc_u32 s27, s37, s27
	s_waitcnt lgkmcnt(0)
	v_cvt_pk_bf16_f32 v29, v30, v31
	ds_read2_b32 v[30:31], v10 offset0:132 offset1:165
	v_lshl_add_u64 v[32:33], s[26:27], 0, v[32:33]
	s_waitcnt lgkmcnt(0)
	v_cvt_pk_bf16_f32 v30, v30, v31
	ds_read2_b32 v[34:35], v10 offset0:198 offset1:231
	s_waitcnt lgkmcnt(0)
	v_cvt_pk_bf16_f32 v31, v34, v35
	v_lshl_add_u64 v[32:33], v[32:33], 0, v[4:5]
	ds_read2_b32 v[34:35], v10 offset0:8 offset1:41
	global_store_dwordx4 v[32:33], v[28:31], off
	s_waitcnt lgkmcnt(0)
	s_nop 0
	v_cvt_pk_bf16_f32 v28, v34, v35
	ds_read2_b32 v[30:31], v10 offset0:74 offset1:107
	s_waitcnt lgkmcnt(0)
	v_cvt_pk_bf16_f32 v29, v30, v31
	ds_read2_b32 v[30:31], v10 offset0:140 offset1:173
	s_waitcnt lgkmcnt(0)
	v_cvt_pk_bf16_f32 v30, v30, v31
	v_add_u32_e32 v31, 0x200, v36
	v_and_b32_e32 v34, 0x3bc0, v31
	v_mov_b32_e32 v35, v3
	v_lshlrev_b32_e32 v34, 1, v34
	v_lshl_add_u64 v[34:35], s[26:27], 0, v[34:35]
	ds_read2_b32 v[32:33], v10 offset0:206 offset1:239
	s_waitcnt lgkmcnt(0)
	v_cvt_pk_bf16_f32 v31, v32, v33
	v_lshl_add_u64 v[34:35], v[34:35], 0, v[4:5]
	ds_read2_b32 v[32:33], v10 offset0:16 offset1:49
	global_store_dwordx4 v[34:35], v[28:31], off
	v_mov_b32_e32 v35, v3
	s_waitcnt lgkmcnt(0)
	v_cvt_pk_bf16_f32 v28, v32, v33
	ds_read2_b32 v[30:31], v10 offset0:82 offset1:115
	s_waitcnt lgkmcnt(0)
	v_cvt_pk_bf16_f32 v29, v30, v31
	ds_read2_b32 v[30:31], v10 offset0:148 offset1:181
	s_waitcnt lgkmcnt(0)
	v_cvt_pk_bf16_f32 v30, v30, v31
	v_add_u32_e32 v31, 0x400, v36
	v_and_b32_e32 v34, 0x3dc0, v31
	v_lshlrev_b32_e32 v34, 1, v34
	v_lshl_add_u64 v[34:35], s[26:27], 0, v[34:35]
	ds_read2_b32 v[32:33], v10 offset0:214 offset1:247
	s_waitcnt lgkmcnt(0)
	v_cvt_pk_bf16_f32 v31, v32, v33
	v_lshl_add_u64 v[34:35], v[34:35], 0, v[4:5]
	ds_read2_b32 v[32:33], v10 offset0:24 offset1:57
	global_store_dwordx4 v[34:35], v[28:31], off
	s_waitcnt lgkmcnt(0)
	s_nop 0
	v_cvt_pk_bf16_f32 v28, v32, v33
	ds_read2_b32 v[30:31], v10 offset0:90 offset1:123
	s_waitcnt lgkmcnt(0)
	v_cvt_pk_bf16_f32 v29, v30, v31
	ds_read2_b32 v[30:31], v10 offset0:156 offset1:189
	s_waitcnt lgkmcnt(0)
	v_cvt_pk_bf16_f32 v30, v30, v31
	v_add_u32_e32 v31, 0x600, v36
	v_and_b32_e32 v31, 0x3fc0, v31
	v_mov_b32_e32 v33, v3
	v_lshlrev_b32_e32 v32, 1, v31
	v_lshl_add_u64 v[32:33], s[26:27], 0, v[32:33]
	v_lshl_add_u64 v[32:33], v[32:33], 0, v[4:5]
	ds_read2_b32 v[34:35], v10 offset0:222 offset1:255
	s_waitcnt lgkmcnt(0)
	v_cvt_pk_bf16_f32 v31, v34, v35
	global_store_dwordx4 v[32:33], v[28:31], off
	s_waitcnt lgkmcnt(0)

.LBB0_25:
	s_andn2_b64 vcc, exec, s[26:27]
	s_cbranch_vccnz .LBB0_14
	s_bfe_u32 s12, s11, 0x70018
	s_add_i32 s12, s11, s12
	s_sext_i32_i16 s13, s12
	s_and_b32 s12, s12, 0xff80
	s_sub_i32 s11, s11, s12
	s_sext_i32_i16 s11, s11
	s_load_dwordx2 s[26:27], s[22:23], 0x40
	s_lshl_b32 s12, s11, 5
	s_lshr_b32 s24, s13, 7
	s_ashr_i32 s13, s13, 7
	s_add_i32 s36, s12, 0x200
	s_add_i32 s37, s12, 0x400
	s_cmp_lt_i32 s11, 48
	s_cselect_b32 s11, s12, s37
	s_mul_i32 s37, s10, 0x2400000
	s_cselect_b32 s36, s12, s36
	s_mul_hi_i32 s12, s10, 0x2400000
	s_waitcnt lgkmcnt(0)
	s_add_u32 s38, s26, s37
	s_addc_u32 s12, s27, s12
	s_mul_hi_i32 s26, s10, 0x1400000
	s_mul_i32 s10, s10, 0x1400000
	s_add_u32 s10, s29, s10
	s_addc_u32 s39, s30, s26
	s_ashr_i32 s37, s36, 31
	s_lshl_b64 s[26:27], s[36:37], 2
	v_lshl_or_b32 v5, s13, 6, v6
	s_add_u32 s26, s38, s26
	s_addc_u32 s27, s12, s27
	v_mul_i32_i24_e32 v30, 0x1200, v5
	v_lshl_add_u64 v[28:29], s[26:27], 0, v[2:3]
	v_ashrrev_i32_e32 v31, 31, v30
	v_lshl_add_u64 v[56:57], v[30:31], 2, v[28:29]
	s_mov_b32 s12, 0x24000
	v_add_co_u32_e32 v32, vcc, s12, v56
	s_mov_b32 s12, 0x48000
	s_nop 0
	v_addc_co_u32_e32 v33, vcc, 0, v57, vcc
	v_add_co_u32_e32 v36, vcc, s12, v56
	s_mov_b32 s12, 0x6c000
	s_nop 0
	v_addc_co_u32_e32 v37, vcc, 0, v57, vcc
	v_add_co_u32_e32 v40, vcc, s12, v56
	s_mov_b32 s12, 0x90000
	s_nop 0
	v_addc_co_u32_e32 v41, vcc, 0, v57, vcc
	v_add_co_u32_e32 v44, vcc, s12, v56
	s_mov_b32 s12, 0xb4000
	s_nop 0
	v_addc_co_u32_e32 v45, vcc, 0, v57, vcc
	v_add_co_u32_e32 v48, vcc, s12, v56
	global_load_dwordx4 v[28:31], v[56:57], off nt
	s_nop 0
	global_load_dwordx4 v[32:35], v[32:33], off nt
	v_addc_co_u32_e32 v49, vcc, 0, v57, vcc
	global_load_dwordx4 v[36:39], v[36:37], off nt
	s_nop 0
	global_load_dwordx4 v[40:43], v[40:41], off nt
	s_nop 0
	global_load_dwordx4 v[44:47], v[44:45], off nt
	s_nop 0
	global_load_dwordx4 v[48:51], v[48:49], off nt
	s_mov_b32 s12, 0xd8000
	v_add_co_u32_e32 v52, vcc, s12, v56
	s_mov_b32 s12, 0xfc000
	s_nop 0
	v_addc_co_u32_e32 v53, vcc, 0, v57, vcc
	global_load_dwordx4 v[52:55], v[52:53], off nt
	v_add_co_u32_e32 v56, vcc, s12, v56
	s_ashr_i32 s36, s11, 8
	s_nop 0
	v_addc_co_u32_e32 v57, vcc, 0, v57, vcc
	global_load_dwordx4 v[56:59], v[56:57], off nt
	s_bfe_i64 s[26:27], s[24:25], 0x100000
	s_ashr_i32 s37, s36, 31
	s_lshl_b64 s[26:27], s[26:27], 15
	s_lshl_b64 s[36:37], s[36:37], 20
	s_add_u32 s10, s10, s36
	s_addc_u32 s12, s39, s37
	s_add_u32 s26, s10, s26
	s_addc_u32 s27, s12, s27
	v_mov_b32_e32 v5, v3
	s_waitcnt vmcnt(7)
	ds_write2_b32 v12, v28, v29 offset1:1
	ds_write2_b32 v12, v30, v31 offset0:2 offset1:3
	s_waitcnt vmcnt(6)
	ds_write2_b32 v13, v32, v33 offset1:1
	ds_write2_b32 v14, v34, v35 offset1:1
	s_waitcnt vmcnt(5)
	ds_write2_b32 v15, v36, v37 offset1:1
	ds_write2_b32 v16, v38, v39 offset1:1
	s_waitcnt vmcnt(4)
	ds_write2_b32 v17, v40, v41 offset1:1
	ds_write2_b32 v18, v42, v43 offset1:1
	s_waitcnt vmcnt(3)
	ds_write2_b32 v19, v44, v45 offset1:1
	ds_write2_b32 v20, v46, v47 offset1:1
	s_waitcnt vmcnt(2)
	ds_write2_b32 v21, v48, v49 offset1:1
	ds_write2_b32 v22, v50, v51 offset1:1
	s_waitcnt vmcnt(1)
	ds_write2_b32 v23, v52, v53 offset1:1
	ds_write2_b32 v24, v54, v55 offset1:1
	s_waitcnt vmcnt(0)
	ds_write2_b32 v25, v56, v57 offset1:1
	ds_write2_b32 v27, v58, v59 offset1:1
	s_waitcnt lgkmcnt(0)
	ds_read2_b32 v[28:29], v10 offset1:33
	s_waitcnt lgkmcnt(0)
	v_cvt_pk_bf16_f32 v28, v28, v29
	v_or_b32_e32 v29, s11, v6
	v_lshlrev_b32_e32 v29, 7, v29
	v_mov_b32_e32 v33, v3
	ds_read2_b32 v[30:31], v10 offset0:66 offset1:99
	v_and_b32_e32 v32, 0x7380, v29
	s_waitcnt lgkmcnt(0)
	v_cvt_pk_bf16_f32 v29, v30, v31
	ds_read2_b32 v[30:31], v10 offset0:132 offset1:165
	v_lshl_add_u64 v[32:33], s[26:27], 0, v[32:33]
	s_waitcnt lgkmcnt(0)
	v_cvt_pk_bf16_f32 v30, v30, v31
	ds_read2_b32 v[34:35], v10 offset0:198 offset1:231
	s_waitcnt lgkmcnt(0)
	v_cvt_pk_bf16_f32 v31, v34, v35
	v_lshl_add_u64 v[32:33], v[32:33], 0, v[4:5]
	ds_read2_b32 v[34:35], v10 offset0:8 offset1:41
	global_store_dwordx4 v[32:33], v[28:31], off
	s_waitcnt lgkmcnt(0)
	s_nop 0
	v_cvt_pk_bf16_f32 v28, v34, v35
	ds_read2_b32 v[30:31], v10 offset0:74 offset1:107
	s_waitcnt lgkmcnt(0)
	v_cvt_pk_bf16_f32 v29, v30, v31
	ds_read2_b32 v[30:31], v10 offset0:140 offset1:173
	s_waitcnt lgkmcnt(0)
	v_cvt_pk_bf16_f32 v30, v30, v31
	v_or_b32_e32 v31, s11, v7
	v_lshlrev_b32_e32 v34, 7, v31
	v_mov_b32_e32 v35, v3
	v_and_b32_e32 v34, 0x7780, v34
	v_lshl_add_u64 v[34:35], s[26:27], 0, v[34:35]
	ds_read2_b32 v[32:33], v10 offset0:206 offset1:239
	s_waitcnt lgkmcnt(0)
	v_cvt_pk_bf16_f32 v31, v32, v33
	v_lshl_add_u64 v[34:35], v[34:35], 0, v[4:5]
	ds_read2_b32 v[32:33], v10 offset0:16 offset1:49
	global_store_dwordx4 v[34:35], v[28:31], off
	v_mov_b32_e32 v35, v3
	s_waitcnt lgkmcnt(0)
	v_cvt_pk_bf16_f32 v28, v32, v33
	ds_read2_b32 v[30:31], v10 offset0:82 offset1:115
	s_waitcnt lgkmcnt(0)
	v_cvt_pk_bf16_f32 v29, v30, v31
	ds_read2_b32 v[30:31], v10 offset0:148 offset1:181
	s_waitcnt lgkmcnt(0)
	v_cvt_pk_bf16_f32 v30, v30, v31
	v_or_b32_e32 v31, s11, v8
	v_lshlrev_b32_e32 v34, 7, v31
	v_and_b32_e32 v34, 0x7b80, v34
	v_lshl_add_u64 v[34:35], s[26:27], 0, v[34:35]
	ds_read2_b32 v[32:33], v10 offset0:214 offset1:247
	s_waitcnt lgkmcnt(0)
	v_cvt_pk_bf16_f32 v31, v32, v33
	v_lshl_add_u64 v[34:35], v[34:35], 0, v[4:5]
	ds_read2_b32 v[32:33], v10 offset0:24 offset1:57
	global_store_dwordx4 v[34:35], v[28:31], off
	s_waitcnt lgkmcnt(0)
	s_nop 0
	v_cvt_pk_bf16_f32 v28, v32, v33
	ds_read2_b32 v[30:31], v10 offset0:90 offset1:123
	s_waitcnt lgkmcnt(0)
	v_cvt_pk_bf16_f32 v29, v30, v31
	ds_read2_b32 v[30:31], v10 offset0:156 offset1:189
	s_waitcnt lgkmcnt(0)
	v_cvt_pk_bf16_f32 v30, v30, v31
	v_or_b32_e32 v31, s11, v9
	v_lshlrev_b32_e32 v31, 7, v31
	v_mov_b32_e32 v33, v3
	v_and_b32_e32 v32, 0x7f80, v31
	v_lshl_add_u64 v[32:33], s[26:27], 0, v[32:33]
	v_lshl_add_u64 v[32:33], v[32:33], 0, v[4:5]
	ds_read2_b32 v[34:35], v10 offset0:222 offset1:255
	s_waitcnt lgkmcnt(0)
	v_cvt_pk_bf16_f32 v31, v34, v35
	global_store_dwordx4 v[32:33], v[28:31], off
	s_waitcnt lgkmcnt(0)
	s_branch .LBB0_14

.LBB0_37:
	s_mov_b32 s10, 0xfffac000
	v_add_co_u32_e32 v36, vcc, s10, v34
	s_mov_b32 s10, 0xfffb8000
	s_nop 0
	v_addc_co_u32_e32 v37, vcc, -1, v35, vcc
	v_add_co_u32_e32 v40, vcc, s10, v34
	s_mov_b32 s10, 0xfffc4000
	s_nop 0
	v_addc_co_u32_e32 v41, vcc, -1, v35, vcc
	v_add_co_u32_e32 v44, vcc, s10, v34
	s_mov_b32 s10, 0xfffd0000
	s_nop 0
	v_addc_co_u32_e32 v45, vcc, -1, v35, vcc
	v_add_co_u32_e32 v48, vcc, s10, v34
	s_mov_b32 s10, 0xfffdc000
	s_nop 0
	v_addc_co_u32_e32 v49, vcc, -1, v35, vcc
	v_add_co_u32_e32 v52, vcc, s10, v34
	s_mov_b32 s10, 0xfffe8000
	s_nop 0
	v_addc_co_u32_e32 v53, vcc, -1, v35, vcc
	v_add_co_u32_e32 v56, vcc, s10, v34
	s_mov_b32 s10, 0xffff4000
	s_nop 0
	v_addc_co_u32_e32 v57, vcc, -1, v35, vcc
	v_add_co_u32_e32 v68, vcc, s10, v34
	v_mov_b32_e32 v27, s8
	global_load_dwordx4 v[22:25], v[34:35], off nt
	v_addc_co_u32_e32 v69, vcc, -1, v35, vcc
	global_load_dwordx4 v[36:39], v[36:37], off nt
	s_nop 0
	global_load_dwordx4 v[40:43], v[40:41], off nt
	s_nop 0
	global_load_dwordx4 v[44:47], v[44:45], off nt
	s_nop 0
	global_load_dwordx4 v[48:51], v[48:49], off nt
	s_nop 0
	global_load_dwordx4 v[52:55], v[52:53], off nt
	s_nop 0
	global_load_dwordx4 v[56:59], v[56:57], off nt
	ds_read_b128 v[60:63], v27
	ds_read_b128 v[64:67], v27 offset:16
	global_load_dwordx4 v[68:71], v[68:69], off nt
	ds_read_b128 v[72:75], v27 offset:8192
	ds_read_b128 v[76:79], v27 offset:8208
	ds_read_b128 v[80:83], v27 offset:16384
	ds_read_b128 v[84:87], v27 offset:16400
	ds_read_b128 v[88:91], v27 offset:24576
	ds_read_b128 v[92:95], v27 offset:24592
	ds_read_b128 v[96:99], v27 offset:32768
	ds_read_b128 v[100:103], v27 offset:32784
	s_waitcnt lgkmcnt(7)
	v_mov_b32_e32 v104, v75
	v_mov_b32_e32 v28, v63
	s_waitcnt lgkmcnt(5)
	v_mov_b32_e32 v106, v83
	s_waitcnt lgkmcnt(3)
	v_mov_b32_e32 v108, v91
	s_waitcnt lgkmcnt(1)
	v_mov_b32_e32 v110, v99
	s_add_i32 s9, s9, 8
	s_add_i32 s8, s8, 32
	s_mov_b64 s[10:11], 0x60000
	v_mov_b32_e32 v112, v67
	v_mov_b32_e32 v114, v79
	v_mov_b32_e32 v116, v87
	v_mov_b32_e32 v118, v95
	s_waitcnt lgkmcnt(0)
	v_mov_b32_e32 v120, v103
	v_lshl_add_u64 v[34:35], v[34:35], 0, s[10:11]
	s_cmpk_gt_u32 s9, 0x77
	s_waitcnt vmcnt(6)
	v_pk_fma_f32 v[20:21], v[38:39], v[60:61], v[20:21] op_sel_hi:[1,0,1]
	v_pk_fma_f32 v[18:19], v[36:37], v[60:61], v[18:19] op_sel_hi:[1,0,1]
	v_pk_fma_f32 v[16:17], v[38:39], v[72:73], v[16:17] op_sel_hi:[1,0,1]
	v_pk_fma_f32 v[14:15], v[36:37], v[72:73], v[14:15] op_sel_hi:[1,0,1]
	v_pk_fma_f32 v[12:13], v[38:39], v[80:81], v[12:13] op_sel_hi:[1,0,1]
	v_pk_fma_f32 v[10:11], v[36:37], v[80:81], v[10:11] op_sel_hi:[1,0,1]
	v_pk_fma_f32 v[8:9], v[38:39], v[88:89], v[8:9] op_sel_hi:[1,0,1]
	v_pk_fma_f32 v[6:7], v[36:37], v[88:89], v[6:7] op_sel_hi:[1,0,1]
	v_pk_fma_f32 v[4:5], v[38:39], v[96:97], v[4:5] op_sel_hi:[1,0,1]
	v_pk_fma_f32 v[2:3], v[36:37], v[96:97], v[2:3] op_sel_hi:[1,0,1]
	s_waitcnt vmcnt(5)
	v_pk_fma_f32 v[20:21], v[42:43], v[60:61], v[20:21] op_sel:[0,1,0]
	v_pk_fma_f32 v[18:19], v[40:41], v[60:61], v[18:19] op_sel:[0,1,0]
	v_pk_fma_f32 v[16:17], v[42:43], v[72:73], v[16:17] op_sel:[0,1,0]
	v_pk_fma_f32 v[14:15], v[40:41], v[72:73], v[14:15] op_sel:[0,1,0]
	v_pk_fma_f32 v[12:13], v[42:43], v[80:81], v[12:13] op_sel:[0,1,0]
	v_pk_fma_f32 v[10:11], v[40:41], v[80:81], v[10:11] op_sel:[0,1,0]
	v_pk_fma_f32 v[8:9], v[42:43], v[88:89], v[8:9] op_sel:[0,1,0]
	v_pk_fma_f32 v[6:7], v[40:41], v[88:89], v[6:7] op_sel:[0,1,0]
	v_pk_fma_f32 v[4:5], v[42:43], v[96:97], v[4:5] op_sel:[0,1,0]
	v_pk_fma_f32 v[2:3], v[40:41], v[96:97], v[2:3] op_sel:[0,1,0]
	s_waitcnt vmcnt(4)
	v_pk_fma_f32 v[20:21], v[46:47], v[62:63], v[20:21] op_sel_hi:[1,0,1]
	v_pk_fma_f32 v[18:19], v[44:45], v[62:63], v[18:19] op_sel_hi:[1,0,1]
	v_pk_fma_f32 v[16:17], v[46:47], v[74:75], v[16:17] op_sel_hi:[1,0,1]
	v_pk_fma_f32 v[14:15], v[44:45], v[74:75], v[14:15] op_sel_hi:[1,0,1]
	v_pk_fma_f32 v[12:13], v[46:47], v[82:83], v[12:13] op_sel_hi:[1,0,1]
	v_pk_fma_f32 v[10:11], v[44:45], v[82:83], v[10:11] op_sel_hi:[1,0,1]
	v_pk_fma_f32 v[8:9], v[46:47], v[90:91], v[8:9] op_sel_hi:[1,0,1]
	v_pk_fma_f32 v[6:7], v[44:45], v[90:91], v[6:7] op_sel_hi:[1,0,1]
	v_pk_fma_f32 v[4:5], v[46:47], v[98:99], v[4:5] op_sel_hi:[1,0,1]
	v_pk_fma_f32 v[2:3], v[44:45], v[98:99], v[2:3] op_sel_hi:[1,0,1]
	s_waitcnt vmcnt(3)
	v_pk_fma_f32 v[20:21], v[50:51], v[28:29], v[20:21] op_sel_hi:[1,0,1]
	v_pk_fma_f32 v[18:19], v[48:49], v[28:29], v[18:19] op_sel_hi:[1,0,1]
	v_pk_fma_f32 v[16:17], v[50:51], v[104:105], v[16:17] op_sel_hi:[1,0,1]
	v_pk_fma_f32 v[14:15], v[48:49], v[104:105], v[14:15] op_sel_hi:[1,0,1]
	v_pk_fma_f32 v[12:13], v[50:51], v[106:107], v[12:13] op_sel_hi:[1,0,1]
	v_pk_fma_f32 v[10:11], v[48:49], v[106:107], v[10:11] op_sel_hi:[1,0,1]
	v_pk_fma_f32 v[8:9], v[50:51], v[108:109], v[8:9] op_sel_hi:[1,0,1]
	v_pk_fma_f32 v[6:7], v[48:49], v[108:109], v[6:7] op_sel_hi:[1,0,1]
	v_pk_fma_f32 v[4:5], v[50:51], v[110:111], v[4:5] op_sel_hi:[1,0,1]
	v_pk_fma_f32 v[2:3], v[48:49], v[110:111], v[2:3] op_sel_hi:[1,0,1]
	s_waitcnt vmcnt(2)
	v_pk_fma_f32 v[20:21], v[54:55], v[64:65], v[20:21] op_sel_hi:[1,0,1]
	v_pk_fma_f32 v[18:19], v[52:53], v[64:65], v[18:19] op_sel_hi:[1,0,1]
	v_pk_fma_f32 v[16:17], v[54:55], v[76:77], v[16:17] op_sel_hi:[1,0,1]
	v_pk_fma_f32 v[14:15], v[52:53], v[76:77], v[14:15] op_sel_hi:[1,0,1]
	v_pk_fma_f32 v[12:13], v[54:55], v[84:85], v[12:13] op_sel_hi:[1,0,1]
	v_pk_fma_f32 v[10:11], v[52:53], v[84:85], v[10:11] op_sel_hi:[1,0,1]
	v_pk_fma_f32 v[8:9], v[54:55], v[92:93], v[8:9] op_sel_hi:[1,0,1]
	v_pk_fma_f32 v[6:7], v[52:53], v[92:93], v[6:7] op_sel_hi:[1,0,1]
	v_pk_fma_f32 v[4:5], v[54:55], v[100:101], v[4:5] op_sel_hi:[1,0,1]
	v_pk_fma_f32 v[2:3], v[52:53], v[100:101], v[2:3] op_sel_hi:[1,0,1]
	s_waitcnt vmcnt(1)
	v_pk_fma_f32 v[20:21], v[58:59], v[64:65], v[20:21] op_sel:[0,1,0]
	v_pk_fma_f32 v[18:19], v[56:57], v[64:65], v[18:19] op_sel:[0,1,0]
	v_pk_fma_f32 v[16:17], v[58:59], v[76:77], v[16:17] op_sel:[0,1,0]
	v_pk_fma_f32 v[14:15], v[56:57], v[76:77], v[14:15] op_sel:[0,1,0]
	v_pk_fma_f32 v[12:13], v[58:59], v[84:85], v[12:13] op_sel:[0,1,0]
	v_pk_fma_f32 v[10:11], v[56:57], v[84:85], v[10:11] op_sel:[0,1,0]
	v_pk_fma_f32 v[8:9], v[58:59], v[92:93], v[8:9] op_sel:[0,1,0]
	v_pk_fma_f32 v[6:7], v[56:57], v[92:93], v[6:7] op_sel:[0,1,0]
	v_pk_fma_f32 v[4:5], v[58:59], v[100:101], v[4:5] op_sel:[0,1,0]
	v_pk_fma_f32 v[2:3], v[56:57], v[100:101], v[2:3] op_sel:[0,1,0]
	s_waitcnt vmcnt(0)
	v_pk_fma_f32 v[20:21], v[70:71], v[66:67], v[20:21] op_sel_hi:[1,0,1]
	v_pk_fma_f32 v[18:19], v[68:69], v[66:67], v[18:19] op_sel_hi:[1,0,1]
	v_pk_fma_f32 v[16:17], v[70:71], v[78:79], v[16:17] op_sel_hi:[1,0,1]
	v_pk_fma_f32 v[14:15], v[68:69], v[78:79], v[14:15] op_sel_hi:[1,0,1]
	v_pk_fma_f32 v[12:13], v[70:71], v[86:87], v[12:13] op_sel_hi:[1,0,1]
	v_pk_fma_f32 v[10:11], v[68:69], v[86:87], v[10:11] op_sel_hi:[1,0,1]
	v_pk_fma_f32 v[8:9], v[70:71], v[94:95], v[8:9] op_sel_hi:[1,0,1]
	v_pk_fma_f32 v[6:7], v[68:69], v[94:95], v[6:7] op_sel_hi:[1,0,1]
	v_pk_fma_f32 v[4:5], v[70:71], v[102:103], v[4:5] op_sel_hi:[1,0,1]
	v_pk_fma_f32 v[2:3], v[68:69], v[102:103], v[2:3] op_sel_hi:[1,0,1]
	v_pk_fma_f32 v[20:21], v[24:25], v[112:113], v[20:21] op_sel_hi:[1,0,1]
	v_pk_fma_f32 v[18:19], v[22:23], v[112:113], v[18:19] op_sel_hi:[1,0,1]
	v_pk_fma_f32 v[16:17], v[24:25], v[114:115], v[16:17] op_sel_hi:[1,0,1]
	v_pk_fma_f32 v[14:15], v[22:23], v[114:115], v[14:15] op_sel_hi:[1,0,1]
	v_pk_fma_f32 v[12:13], v[24:25], v[116:117], v[12:13] op_sel_hi:[1,0,1]
	v_pk_fma_f32 v[10:11], v[22:23], v[116:117], v[10:11] op_sel_hi:[1,0,1]
	v_pk_fma_f32 v[8:9], v[24:25], v[118:119], v[8:9] op_sel_hi:[1,0,1]
	v_pk_fma_f32 v[6:7], v[22:23], v[118:119], v[6:7] op_sel_hi:[1,0,1]
	v_pk_fma_f32 v[4:5], v[24:25], v[120:121], v[4:5] op_sel_hi:[1,0,1]
	v_pk_fma_f32 v[2:3], v[22:23], v[120:121], v[2:3] op_sel_hi:[1,0,1]
	s_cbranch_scc0 .LBB0_37
	s_mul_i32 s7, s7, 20
	s_mul_i32 s6, s6, 5
	s_add_i32 s7, s7, s6
	v_lshl_add_u64 v[22:23], s[24:25], 2, v[30:31]
	v_mad_i64_i32 v[22:23], s[6:7], s7, v1, v[22:23]
	global_store_dwordx4 v[22:23], v[18:21], off
	s_add_i32 s0, s0, s1
	s_cmpk_gt_i32 s0, 0xbff
	v_add_co_u32_e32 v18, vcc, 0xc000, v22
	s_nop 1
	v_addc_co_u32_e32 v19, vcc, 0, v23, vcc
	global_store_dwordx4 v[18:19], v[14:17], off
	s_nop 1
	v_add_co_u32_e32 v14, vcc, 0x18000, v22
	s_nop 1
	v_addc_co_u32_e32 v15, vcc, 0, v23, vcc
	global_store_dwordx4 v[14:15], v[10:13], off
	s_nop 1
	v_add_co_u32_e32 v10, vcc, 0x24000, v22
	s_nop 1
	v_addc_co_u32_e32 v11, vcc, 0, v23, vcc
	global_store_dwordx4 v[10:11], v[6:9], off
	s_nop 1
	v_add_co_u32_e32 v6, vcc, 0x30000, v22
	s_nop 1
	v_addc_co_u32_e32 v7, vcc, 0, v23, vcc
	global_store_dwordx4 v[6:7], v[2:5], off
	s_cbranch_scc0 .LBB0_36

.LBB0_1290:
	global_load_dwordx4 v[22:25], v[10:11], off offset:-1024
	global_load_dwordx4 v[26:29], v[10:11], off
	global_load_dwordx4 v[30:33], v[10:11], off offset:1024
	global_load_dwordx4 v[34:37], v[10:11], off offset:-2048
	global_load_dwordx4 v[38:41], v[0:1], off
	s_add_i32 s8, s8, s2
	v_lshl_add_u64 v[10:11], v[10:11], 0, s[4:5]
	s_cmpk_lt_i32 s8, 0x4000
	s_waitcnt vmcnt(0)
	v_lshlrev_b32_e32 v42, 16, v24
	v_and_b32_e32 v43, 0xffff0000, v24
	v_and_b32_e32 v55, 0xffff0000, v23
	v_lshlrev_b32_e32 v49, 16, v36
	v_and_b32_e32 v51, 0xffff0000, v36
	v_and_b32_e32 v50, 0xffff0000, v34
	v_lshlrev_b32_e32 v53, 16, v37
	v_and_b32_e32 v37, 0xffff0000, v37
	v_and_b32_e32 v36, 0xffff0000, v35
	v_lshlrev_b32_e32 v48, 16, v34
	v_lshlrev_b32_e32 v52, 16, v35
	v_lshlrev_b32_e32 v35, 16, v23
	v_lshlrev_b32_e32 v34, 16, v22
	v_and_b32_e32 v54, 0xffff0000, v22
	v_lshlrev_b32_e32 v56, 16, v25
	v_and_b32_e32 v57, 0xffff0000, v25
	v_pk_mul_f32 v[22:23], v[50:51], v[50:51]
	v_pk_mul_f32 v[24:25], v[36:37], v[36:37]
	v_lshlrev_b32_e32 v44, 16, v26
	v_pk_mul_f32 v[62:63], v[54:55], v[54:55]
	v_pk_fma_f32 v[22:23], v[48:49], v[48:49], v[22:23]
	v_pk_fma_f32 v[24:25], v[52:53], v[52:53], v[24:25]
	v_mul_f32_e32 v45, v42, v42
	v_mul_f32_e32 v65, v43, v43
	v_mul_f32_e32 v66, v56, v56
	v_mov_b32_e32 v64, v44
	v_pk_fma_f32 v[62:63], v[34:35], v[34:35], v[62:63]
	v_pk_add_f32 v[22:23], v[22:23], v[24:25]
	v_and_b32_e32 v82, 0xffff0000, v26
	v_lshlrev_b32_e32 v26, 16, v27
	v_and_b32_e32 v27, 0xffff0000, v27
	v_pk_fma_f32 v[66:67], v[56:57], v[56:57], v[66:67] op_sel_hi:[1,1,0]
	v_pk_add_f32 v[64:65], v[44:45], v[64:65]
	v_pk_add_f32 v[24:25], v[62:63], v[62:63] op_sel_hi:[0,1]
	v_pk_add_f32 v[22:23], v[22:23], v[22:23] op_sel_hi:[0,1]
	v_lshlrev_b32_e32 v59, 16, v29
	v_lshlrev_b32_e32 v58, 16, v28
	v_and_b32_e32 v29, 0xffff0000, v29
	v_and_b32_e32 v28, 0xffff0000, v28
	v_mul_f32_e32 v68, v44, v44
	v_mul_f32_e32 v66, v82, v82
	v_mov_b32_e32 v69, v65
	v_mul_f32_e32 v24, v27, v27
	v_mul_f32_e32 v22, v26, v26
	v_lshlrev_b32_e32 v46, 16, v30
	v_and_b32_e32 v47, 0xffff0000, v30
	v_lshlrev_b32_e32 v30, 16, v32
	v_lshlrev_b32_e32 v60, 16, v31
	v_pk_mul_f32 v[70:71], v[28:29], v[28:29]
	v_pk_add_f32 v[64:65], v[68:69], v[66:67]
	v_pk_add_f32 v[22:23], v[22:23], v[24:25]
	v_and_b32_e32 v61, 0xffff0000, v31
	v_mul_f32_e32 v31, v46, v46
	v_mul_f32_e32 v73, v47, v47
	v_mul_f32_e32 v74, v60, v60
	v_mov_b32_e32 v72, v30
	v_pk_fma_f32 v[70:71], v[58:59], v[58:59], v[70:71]
	v_pk_add_f32 v[22:23], v[64:65], v[22:23]
	v_and_b32_e32 v83, 0xffff0000, v32
	v_lshlrev_b32_e32 v32, 16, v33
	v_and_b32_e32 v33, 0xffff0000, v33
	v_pk_fma_f32 v[74:75], v[60:61], v[60:61], v[74:75] op_sel_hi:[1,1,0]
	v_pk_add_f32 v[72:73], v[30:31], v[72:73]
	v_pk_add_f32 v[62:63], v[70:71], v[70:71] op_sel_hi:[0,1]
	v_pk_add_f32 v[22:23], v[22:23], v[22:23] op_sel_hi:[0,1]
	v_mul_f32_e32 v76, v30, v30
	v_mul_f32_e32 v74, v83, v83
	v_mov_b32_e32 v77, v73
	v_mul_f32_e32 v62, v32, v32
	v_mul_f32_e32 v22, v33, v33
	v_pk_add_f32 v[66:67], v[76:77], v[74:75]
	v_pk_add_f32 v[22:23], v[62:63], v[22:23]
	v_mov_b32_e32 v81, v36
	v_pk_add_f32 v[22:23], v[66:67], v[22:23]
	v_mov_b32_e32 v78, v48
	v_add_f32_e32 v22, v22, v23
	ds_bpermute_b32 v23, v14, v22
	v_mov_b32_e32 v79, v50
	v_mov_b32_e32 v80, v52
	v_mov_b32_e32 v50, v49
	v_mov_b32_e32 v45, v82
	s_waitcnt lgkmcnt(0)
	v_add_f32_e32 v22, v22, v23
	ds_bpermute_b32 v23, v15, v22
	s_waitcnt lgkmcnt(0)
	v_add_f32_e32 v22, v22, v23
	ds_bpermute_b32 v23, v16, v22
	s_waitcnt lgkmcnt(0)
	v_add_f32_e32 v22, v22, v23
	ds_bpermute_b32 v23, v17, v22
	s_waitcnt lgkmcnt(0)
	v_add_f32_e32 v22, v22, v23
	ds_bpermute_b32 v23, v18, v22
	s_waitcnt lgkmcnt(0)
	v_add_f32_e32 v22, v22, v23
	ds_bpermute_b32 v23, v19, v22
	s_waitcnt lgkmcnt(0)
	v_add_f32_e32 v22, v22, v23
	v_fmamk_f32 v22, v22, 0x3a000000, v20
	v_mul_f32_e32 v23, 0x4f800000, v22
	v_cmp_gt_f32_e32 vcc, s3, v22
	s_nop 1
	v_cndmask_b32_e32 v22, v22, v23, vcc
	v_sqrt_f32_e32 v23, v22
	s_nop 0
	v_add_u32_e32 v24, -1, v23
	v_add_u32_e32 v25, 1, v23
	v_fma_f32 v31, -v24, v23, v22
	v_fma_f32 v36, -v25, v23, v22
	v_cmp_ge_f32_e64 s[0:1], 0, v31
	s_nop 1
	v_cndmask_b32_e64 v23, v23, v24, s[0:1]
	v_cmp_lt_f32_e64 s[0:1], 0, v36
	s_nop 1
	v_cndmask_b32_e64 v23, v23, v25, s[0:1]
	v_mul_f32_e32 v24, 0x37800000, v23
	v_cndmask_b32_e32 v23, v23, v24, vcc
	v_cmp_class_f32_e32 vcc, v22, v21
	s_nop 1
	v_cndmask_b32_e32 v22, v23, v22, vcc
	v_div_scale_f32 v23, s[0:1], v22, v22, 1.0
	v_rcp_f32_e32 v25, v23
	v_div_scale_f32 v24, vcc, 1.0, v22, 1.0
	v_fma_f32 v31, -v23, v25, 1.0
	v_fmac_f32_e32 v25, v31, v25
	v_mul_f32_e32 v31, v24, v25
	v_fma_f32 v36, -v23, v31, v24
	v_fmac_f32_e32 v31, v36, v25
	v_fma_f32 v23, -v23, v31, v24
	v_div_fmas_f32 v23, v23, v25, v31
	v_div_fixup_f32 v48, v23, v22, 1.0
	v_pk_mul_f32 v[22:23], v[78:79], v[48:49] op_sel_hi:[1,0]
	v_pk_mul_f32 v[24:25], v[80:81], v[48:49] op_sel_hi:[1,0]
	v_pk_mul_f32 v[22:23], v[38:39], v[22:23]
	v_pk_mul_f32 v[24:25], v[40:41], v[24:25]
	global_store_dwordx4 v[12:13], v[22:25], off offset:-4096 nt
	global_load_dwordx4 v[22:25], v[0:1], off offset:16
	v_mov_b32_e32 v36, v53
	v_pk_mul_f32 v[36:37], v[36:37], v[48:49] op_sel_hi:[1,0]
	v_pk_mul_f32 v[38:39], v[50:51], v[48:49] op_sel_hi:[1,0]
	v_pk_mul_f32 v[26:27], v[26:27], v[48:49] op_sel_hi:[1,0]
	v_mov_b32_e32 v31, v83
	s_waitcnt vmcnt(0)
	v_pk_mul_f32 v[22:23], v[22:23], v[38:39]
	v_pk_mul_f32 v[24:25], v[24:25], v[36:37]
	global_store_dwordx4 v[12:13], v[22:25], off offset:-4080 nt
	global_load_dwordx4 v[22:25], v[0:1], off offset:2048
	v_mov_b32_e32 v36, v35
	v_mov_b32_e32 v37, v55
	v_mov_b32_e32 v35, v54
	v_pk_mul_f32 v[36:37], v[48:49], v[36:37] op_sel_hi:[0,1]
	v_pk_mul_f32 v[34:35], v[48:49], v[34:35] op_sel_hi:[0,1]
	s_waitcnt vmcnt(0)
	v_pk_mul_f32 v[22:23], v[22:23], v[34:35]
	v_pk_mul_f32 v[24:25], v[24:25], v[36:37]
	global_store_dwordx4 v[12:13], v[22:25], off offset:-2048 nt
	global_load_dwordx4 v[22:25], v[0:1], off offset:2064
	v_pk_mul_f32 v[34:35], v[56:57], v[48:49] op_sel_hi:[1,0]
	v_pk_mul_f32 v[36:37], v[42:43], v[48:49] op_sel_hi:[1,0]
	s_waitcnt vmcnt(0)
	v_pk_mul_f32 v[24:25], v[24:25], v[34:35]
	v_pk_mul_f32 v[22:23], v[22:23], v[36:37]
	global_store_dwordx4 v[12:13], v[22:25], off offset:-2032 nt
	global_load_dwordx4 v[22:25], v[2:3], off
	v_pk_mul_f32 v[34:35], v[44:45], v[48:49] op_sel_hi:[1,0]
	s_waitcnt vmcnt(0)
	v_pk_mul_f32 v[24:25], v[24:25], v[26:27]
	v_pk_mul_f32 v[22:23], v[22:23], v[34:35]
	global_store_dwordx4 v[12:13], v[22:25], off nt
	global_load_dwordx4 v[22:25], v[4:5], off
	v_mov_b32_e32 v26, v59
	v_mov_b32_e32 v27, v29
	v_mov_b32_e32 v59, v28
	v_pk_mul_f32 v[26:27], v[48:49], v[26:27] op_sel_hi:[0,1]
	v_pk_mul_f32 v[28:29], v[48:49], v[58:59] op_sel_hi:[0,1]
	s_waitcnt vmcnt(0)
	v_pk_mul_f32 v[22:23], v[22:23], v[28:29]
	v_pk_mul_f32 v[24:25], v[24:25], v[26:27]
	global_store_dwordx4 v[12:13], v[22:25], off offset:16 nt
	global_load_dwordx4 v[22:25], v[6:7], off
	v_pk_mul_f32 v[26:27], v[60:61], v[48:49] op_sel_hi:[1,0]
	v_pk_mul_f32 v[28:29], v[46:47], v[48:49] op_sel_hi:[1,0]
	s_waitcnt vmcnt(0)
	v_pk_mul_f32 v[24:25], v[24:25], v[26:27]
	v_pk_mul_f32 v[22:23], v[22:23], v[28:29]
	global_store_dwordx4 v[12:13], v[22:25], off offset:2048 nt
	global_load_dwordx4 v[22:25], v[8:9], off
	v_pk_mul_f32 v[26:27], v[32:33], v[48:49] op_sel_hi:[1,0]
	v_pk_mul_f32 v[28:29], v[30:31], v[48:49] op_sel_hi:[1,0]
	s_waitcnt vmcnt(0)
	v_pk_mul_f32 v[24:25], v[24:25], v[26:27]
	v_pk_mul_f32 v[22:23], v[22:23], v[28:29]
	global_store_dwordx4 v[12:13], v[22:25], off offset:2064 nt
	v_lshl_add_u64 v[12:13], v[12:13], 0, s[6:7]
	s_cbranch_scc1 .LBB0_1290
